# attention loop: packed fp32 row-sum adds split into scalar v_add_f32 chains (asm guide 7.5)
# speedup vs baseline: 1.0124x; 1.0124x over previous
.LBB0_280:
	s_waitcnt lgkmcnt(5)
	v_mfma_f32_32x32x16_bf16 v[66:81], v[166:169], v[134:137], v[66:81]
	s_waitcnt lgkmcnt(4)
	v_mfma_f32_32x32x16_bf16 v[82:97], v[162:165], v[134:137], v[82:97]
	s_waitcnt lgkmcnt(3)
	v_mfma_f32_32x32x16_bf16 v[66:81], v[158:161], v[138:141], v[66:81]
	s_waitcnt lgkmcnt(2)
	v_mfma_f32_32x32x16_bf16 v[82:97], v[154:157], v[138:141], v[82:97]
	s_waitcnt lgkmcnt(1)
	v_mfma_f32_32x32x16_bf16 v[66:81], v[150:153], v[142:145], v[66:81]
	s_waitcnt lgkmcnt(0)
	v_mfma_f32_32x32x16_bf16 v[82:97], v[146:149], v[142:145], v[82:97]
	v_add_f32_e32 v146, v114, v115
	v_add_f32_e32 v147, v116, v117
	v_add_f32_e32 v148, v118, v119
	v_add_f32_e32 v149, v120, v121
	v_add_f32_e32 v146, v146, v122
	v_add_f32_e32 v147, v147, v123
	v_add_f32_e32 v148, v148, v124
	v_add_f32_e32 v149, v149, v125
	v_add_f32_e32 v146, v146, v126
	v_add_f32_e32 v147, v147, v127
	v_add_f32_e32 v148, v148, v128
	v_add_f32_e32 v149, v149, v129
	v_add_f32_e32 v146, v146, v98
	v_add_f32_e32 v147, v147, v99
	v_add_f32_e32 v148, v148, v100
	v_add_f32_e32 v149, v149, v101
	v_add_f32_e32 v146, v146, v102
	v_add_f32_e32 v147, v147, v103
	v_add_f32_e32 v148, v148, v104
	v_add_f32_e32 v149, v149, v105
	v_add_f32_e32 v146, v146, v106
	v_add_f32_e32 v147, v147, v107
	v_add_f32_e32 v148, v148, v108
	v_add_f32_e32 v149, v149, v109
	v_add_f32_e32 v146, v146, v110
	v_add_f32_e32 v147, v147, v111
	v_add_f32_e32 v148, v148, v112
	v_add_f32_e32 v149, v149, v113
	v_add_f32_e32 v146, v146, v147
	v_add_f32_e32 v148, v148, v149
	v_cvt_pk_bf16_f32 v113, v112, v113
	v_cvt_pk_bf16_f32 v112, v110, v111
	v_cvt_pk_bf16_f32 v111, v108, v109
	v_cvt_pk_bf16_f32 v110, v106, v107
	v_add_f32_e32 v146, v146, v148
	v_cvt_pk_bf16_f32 v109, v104, v105
	v_cvt_pk_bf16_f32 v108, v102, v103
	v_cvt_pk_bf16_f32 v107, v100, v101
	v_cvt_pk_bf16_f32 v106, v98, v99
	v_cvt_pk_bf16_f32 v98, v114, v115
	v_cvt_pk_bf16_f32 v99, v116, v117
	v_cvt_pk_bf16_f32 v100, v118, v119
	v_cvt_pk_bf16_f32 v101, v120, v121
	v_cvt_pk_bf16_f32 v102, v122, v123
	v_cvt_pk_bf16_f32 v103, v124, v125
	v_cvt_pk_bf16_f32 v104, v126, v127
	v_cvt_pk_bf16_f32 v105, v128, v129
	v_add_f32_e32 v213, v146, v0
	ds_read_b128 v[114:117], v208 offset:49152
	ds_read_b128 v[118:121], v208 offset:53248
	ds_read_b128 v[122:125], v208 offset:57344
	ds_read_b128 v[126:129], v208 offset:61440
	ds_read_b128 v[150:153], v209 offset:53248
	ds_read_b128 v[146:149], v209 offset:49152
	ds_read_b128 v[154:157], v209 offset:57344
	ds_read_b128 v[158:161], v209 offset:61440
	s_and_b32 s0, s77, 0x3f0000
	s_lshl_b32 s22, s0, 1
	s_mov_b32 m0, s73
	v_lshl_add_u64 v[164:165], v[188:189], 0, s[22:23]
	global_load_lds_dwordx4 v[164:165], off
	v_lshl_add_u64 v[164:165], v[192:193], 0, s[22:23]
	s_mov_b32 m0, s31
	s_lshl_b32 s22, s15, 1
	global_load_lds_dwordx4 v[164:165], off
	v_lshl_add_u64 v[164:165], v[190:191], 0, s[22:23]
	s_mov_b32 m0, s71
	global_load_lds_dwordx4 v[164:165], off
	v_lshl_add_u64 v[164:165], v[194:195], 0, s[22:23]
	s_mov_b32 m0, s72
	s_nop 0
	global_load_lds_dwordx4 v[164:165], off
	s_waitcnt lgkmcnt(0)
	v_mfma_f32_32x32x16_bf16 v[50:65], v[98:101], v[114:117], v[50:65]
	ds_read_b128 v[114:117], v210 offset:53248
	v_exp_f32_e32 v66, v66
	v_exp_f32_e32 v67, v67
	v_mfma_f32_32x32x16_bf16 v[34:49], v[98:101], v[118:121], v[34:49]
	ds_read_b128 v[118:121], v210 offset:57344
	v_exp_f32_e32 v68, v68
	v_exp_f32_e32 v69, v69
	v_mfma_f32_32x32x16_bf16 v[18:33], v[98:101], v[122:125], v[18:33]
	ds_read_b128 v[122:125], v210 offset:61440
	v_exp_f32_e32 v70, v70
	v_exp_f32_e32 v71, v71
	v_mfma_f32_32x32x16_bf16 v[2:17], v[98:101], v[126:129], v[2:17]
	ds_read_b128 v[98:101], v210 offset:49152
	v_exp_f32_e32 v72, v72
	v_exp_f32_e32 v73, v73
	v_mfma_f32_32x32x16_bf16 v[50:65], v[102:105], v[146:149], v[50:65]
	ds_read_b128 v[126:129], v212 offset:53248
	v_exp_f32_e32 v74, v74
	v_exp_f32_e32 v75, v75
	v_mfma_f32_32x32x16_bf16 v[34:49], v[102:105], v[150:153], v[34:49]
	ds_read_b128 v[146:149], v212 offset:57344
	v_exp_f32_e32 v76, v76
	v_exp_f32_e32 v77, v77
	v_mfma_f32_32x32x16_bf16 v[18:33], v[102:105], v[154:157], v[18:33]
	ds_read_b128 v[150:153], v212 offset:61440
	v_exp_f32_e32 v78, v78
	v_exp_f32_e32 v79, v79
	v_mfma_f32_32x32x16_bf16 v[2:17], v[102:105], v[158:161], v[2:17]
	ds_read_b128 v[102:105], v212 offset:49152
	v_exp_f32_e32 v80, v80
	v_exp_f32_e32 v81, v81
	s_waitcnt lgkmcnt(0)
	v_mfma_f32_32x32x16_bf16 v[50:65], v[106:109], v[98:101], v[50:65]
	v_exp_f32_e32 v82, v82
	v_exp_f32_e32 v83, v83
	v_mfma_f32_32x32x16_bf16 v[34:49], v[106:109], v[114:117], v[34:49]
	v_exp_f32_e32 v84, v84
	v_exp_f32_e32 v85, v85
	v_mfma_f32_32x32x16_bf16 v[18:33], v[106:109], v[118:121], v[18:33]
	v_exp_f32_e32 v86, v86
	v_exp_f32_e32 v87, v87
	v_mfma_f32_32x32x16_bf16 v[2:17], v[106:109], v[122:125], v[2:17]
	v_exp_f32_e32 v88, v88
	v_exp_f32_e32 v89, v89
	v_mfma_f32_32x32x16_bf16 v[50:65], v[110:113], v[102:105], v[50:65]
	v_exp_f32_e32 v90, v90
	v_exp_f32_e32 v91, v91
	v_mfma_f32_32x32x16_bf16 v[34:49], v[110:113], v[126:129], v[34:49]
	v_exp_f32_e32 v92, v92
	v_exp_f32_e32 v93, v93
	v_mfma_f32_32x32x16_bf16 v[18:33], v[110:113], v[146:149], v[18:33]
	v_exp_f32_e32 v94, v94
	v_exp_f32_e32 v95, v95
	v_mfma_f32_32x32x16_bf16 v[2:17], v[110:113], v[150:153], v[2:17]
	v_exp_f32_e32 v96, v96
	v_exp_f32_e32 v97, v97
	s_waitcnt vmcnt(0)
	s_add_i32 s76, s76, 2
	s_add_i32 s77, s77, 0x20000
	s_cmp_gt_u32 s76, 61
	s_waitcnt vmcnt(0)
	s_barrier
	s_cbranch_scc1 .LBB0_295

.LBB0_288:
	s_waitcnt lgkmcnt(5)
	v_mfma_f32_32x32x16_bf16 v[114:129], v[166:169], v[134:137], v[114:129]
	s_waitcnt lgkmcnt(4)
	v_mfma_f32_32x32x16_bf16 v[98:113], v[162:165], v[134:137], v[98:113]
	s_waitcnt lgkmcnt(3)
	v_mfma_f32_32x32x16_bf16 v[114:129], v[158:161], v[138:141], v[114:129]
	s_waitcnt lgkmcnt(2)
	v_mfma_f32_32x32x16_bf16 v[98:113], v[154:157], v[138:141], v[98:113]
	s_waitcnt lgkmcnt(1)
	v_mfma_f32_32x32x16_bf16 v[114:129], v[150:153], v[142:145], v[114:129]
	s_waitcnt lgkmcnt(0)
	v_mfma_f32_32x32x16_bf16 v[98:113], v[146:149], v[142:145], v[98:113]
	v_add_f32_e32 v146, v66, v67
	v_add_f32_e32 v147, v68, v69
	v_add_f32_e32 v148, v70, v71
	v_add_f32_e32 v149, v72, v73
	v_add_f32_e32 v146, v146, v74
	v_add_f32_e32 v147, v147, v75
	v_add_f32_e32 v148, v148, v76
	v_add_f32_e32 v149, v149, v77
	v_add_f32_e32 v146, v146, v78
	v_add_f32_e32 v147, v147, v79
	v_add_f32_e32 v148, v148, v80
	v_add_f32_e32 v149, v149, v81
	v_add_f32_e32 v146, v146, v82
	v_add_f32_e32 v147, v147, v83
	v_add_f32_e32 v148, v148, v84
	v_add_f32_e32 v149, v149, v85
	v_add_f32_e32 v146, v146, v86
	v_add_f32_e32 v147, v147, v87
	v_add_f32_e32 v148, v148, v88
	v_add_f32_e32 v149, v149, v89
	v_add_f32_e32 v146, v146, v90
	v_add_f32_e32 v147, v147, v91
	v_add_f32_e32 v148, v148, v92
	v_add_f32_e32 v149, v149, v93
	v_add_f32_e32 v146, v146, v94
	v_add_f32_e32 v147, v147, v95
	v_add_f32_e32 v148, v148, v96
	v_add_f32_e32 v149, v149, v97
	v_add_f32_e32 v146, v146, v147
	v_add_f32_e32 v148, v148, v149
	v_cvt_pk_bf16_f32 v66, v66, v67
	v_cvt_pk_bf16_f32 v67, v68, v69
	v_cvt_pk_bf16_f32 v68, v70, v71
	v_cvt_pk_bf16_f32 v69, v72, v73
	v_add_f32_e32 v146, v146, v148
	v_cvt_pk_bf16_f32 v70, v74, v75
	v_cvt_pk_bf16_f32 v71, v76, v77
	v_cvt_pk_bf16_f32 v72, v78, v79
	v_cvt_pk_bf16_f32 v73, v80, v81
	v_cvt_pk_bf16_f32 v74, v82, v83
	v_cvt_pk_bf16_f32 v75, v84, v85
	v_cvt_pk_bf16_f32 v76, v86, v87
	v_cvt_pk_bf16_f32 v77, v88, v89
	v_cvt_pk_bf16_f32 v78, v90, v91
	v_cvt_pk_bf16_f32 v79, v92, v93
	v_cvt_pk_bf16_f32 v80, v94, v95
	v_cvt_pk_bf16_f32 v81, v96, v97
	v_add_f32_e32 v0, v146, v213
	ds_read_b128 v[82:85], v208 offset:32768
	ds_read_b128 v[86:89], v208 offset:36864
	ds_read_b128 v[90:93], v208 offset:40960
	ds_read_b128 v[94:97], v208 offset:45056
	ds_read_b128 v[146:149], v209 offset:32768
	ds_read_b128 v[150:153], v209 offset:36864
	ds_read_b128 v[154:157], v209 offset:40960
	ds_read_b128 v[158:161], v209 offset:45056
	s_add_i32 s14, s77, 0xffff0000
	s_and_b32 s14, s14, 0x3e0000
	s_lshl_b32 s22, s14, 1
	s_mov_b32 m0, s70
	v_lshl_add_u64 v[164:165], v[188:189], 0, s[22:23]
	global_load_lds_dwordx4 v[164:165], off
	v_lshl_add_u64 v[164:165], v[192:193], 0, s[22:23]
	s_mov_b32 m0, s29
	s_lshl_b32 s22, s80, 1
	global_load_lds_dwordx4 v[164:165], off
	v_lshl_add_u64 v[164:165], v[190:191], 0, s[22:23]
	s_add_i32 m0, s70, 0xc000
	global_load_lds_dwordx4 v[164:165], off
	v_lshl_add_u64 v[164:165], v[194:195], 0, s[22:23]
	s_add_i32 m0, s70, 0xc400
	s_nop 0
	global_load_lds_dwordx4 v[164:165], off
	s_waitcnt lgkmcnt(0)
	v_mfma_f32_32x32x16_bf16 v[50:65], v[66:69], v[82:85], v[50:65]
	ds_read_b128 v[82:85], v210 offset:32768
	v_exp_f32_e32 v114, v114
	v_exp_f32_e32 v115, v115
	v_mfma_f32_32x32x16_bf16 v[34:49], v[66:69], v[86:89], v[34:49]
	ds_read_b128 v[86:89], v210 offset:36864
	v_exp_f32_e32 v116, v116
	v_exp_f32_e32 v117, v117
	v_mfma_f32_32x32x16_bf16 v[18:33], v[66:69], v[90:93], v[18:33]
	ds_read_b128 v[90:93], v210 offset:40960
	v_exp_f32_e32 v118, v118
	v_exp_f32_e32 v119, v119
	v_mfma_f32_32x32x16_bf16 v[2:17], v[66:69], v[94:97], v[2:17]
	ds_read_b128 v[66:69], v210 offset:45056
	v_exp_f32_e32 v120, v120
	v_exp_f32_e32 v121, v121
	v_mfma_f32_32x32x16_bf16 v[50:65], v[70:73], v[146:149], v[50:65]
	ds_read_b128 v[94:97], v212 offset:32768
	v_exp_f32_e32 v122, v122
	v_exp_f32_e32 v123, v123
	v_mfma_f32_32x32x16_bf16 v[34:49], v[70:73], v[150:153], v[34:49]
	ds_read_b128 v[146:149], v212 offset:36864
	v_exp_f32_e32 v124, v124
	v_exp_f32_e32 v125, v125
	v_mfma_f32_32x32x16_bf16 v[18:33], v[70:73], v[154:157], v[18:33]
	ds_read_b128 v[150:153], v212 offset:40960
	v_exp_f32_e32 v126, v126
	v_exp_f32_e32 v127, v127
	v_mfma_f32_32x32x16_bf16 v[2:17], v[70:73], v[158:161], v[2:17]
	ds_read_b128 v[70:73], v212 offset:45056
	v_exp_f32_e32 v128, v128
	v_exp_f32_e32 v129, v129
	s_waitcnt lgkmcnt(0)
	v_mfma_f32_32x32x16_bf16 v[50:65], v[74:77], v[82:85], v[50:65]
	v_exp_f32_e32 v98, v98
	v_exp_f32_e32 v99, v99
	v_mfma_f32_32x32x16_bf16 v[34:49], v[74:77], v[86:89], v[34:49]
	v_exp_f32_e32 v100, v100
	v_exp_f32_e32 v101, v101
	v_mfma_f32_32x32x16_bf16 v[18:33], v[74:77], v[90:93], v[18:33]
	v_exp_f32_e32 v102, v102
	v_exp_f32_e32 v103, v103
	v_mfma_f32_32x32x16_bf16 v[2:17], v[74:77], v[66:69], v[2:17]
	v_exp_f32_e32 v104, v104
	v_exp_f32_e32 v105, v105
	v_mfma_f32_32x32x16_bf16 v[50:65], v[78:81], v[94:97], v[50:65]
	v_exp_f32_e32 v106, v106
	v_exp_f32_e32 v107, v107
	v_mfma_f32_32x32x16_bf16 v[34:49], v[78:81], v[146:149], v[34:49]
	v_exp_f32_e32 v108, v108
	v_exp_f32_e32 v109, v109
	v_mfma_f32_32x32x16_bf16 v[18:33], v[78:81], v[150:153], v[18:33]
	v_exp_f32_e32 v110, v110
	v_exp_f32_e32 v111, v111
	v_mfma_f32_32x32x16_bf16 v[2:17], v[78:81], v[70:73], v[2:17]
	v_exp_f32_e32 v112, v112
	v_exp_f32_e32 v113, v113
	s_and_b64 s[0:1], s[0:1], exec
	s_waitcnt vmcnt(0)
	s_cselect_b32 s14, 1, 2
	s_and_b64 s[0:1], s[40:41], exec
	s_cselect_b32 s14, s14, 0
	s_cmp_eq_u32 s14, s79
	s_waitcnt vmcnt(0)
	s_barrier
	s_cbranch_scc1 .LBB0_290
	s_cmp_eq_u32 s79, 0
	s_cselect_b64 vcc, -1, 0
	s_cmp_eq_u32 s79, 2
	s_cselect_b64 s[0:1], -1, 0
	v_cndmask_b32_e64 v66, 0, v201, s[0:1]
	s_cmp_eq_u32 s14, 2
	v_cndmask_b32_e32 v66, v66, v200, vcc
	s_cselect_b64 vcc, -1, 0
	v_cndmask_b32_e32 v67, 0, v201, vcc
	v_cndmask_b32_e64 v67, v200, v67, s[40:41]
	v_sub_f32_e32 v66, v66, v67
	v_exp_f32_e32 v66, v66
	s_nop 0
	v_pk_mul_f32 v[64:65], v[66:67], v[64:65] op_sel_hi:[0,1]
	v_pk_mul_f32 v[62:63], v[66:67], v[62:63] op_sel_hi:[0,1]
	v_pk_mul_f32 v[60:61], v[66:67], v[60:61] op_sel_hi:[0,1]
	v_pk_mul_f32 v[58:59], v[66:67], v[58:59] op_sel_hi:[0,1]
	v_pk_mul_f32 v[56:57], v[66:67], v[56:57] op_sel_hi:[0,1]
	v_pk_mul_f32 v[54:55], v[66:67], v[54:55] op_sel_hi:[0,1]
	v_pk_mul_f32 v[52:53], v[66:67], v[52:53] op_sel_hi:[0,1]
	v_pk_mul_f32 v[50:51], v[66:67], v[50:51] op_sel_hi:[0,1]
	v_pk_mul_f32 v[48:49], v[66:67], v[48:49] op_sel_hi:[0,1]
	v_pk_mul_f32 v[46:47], v[66:67], v[46:47] op_sel_hi:[0,1]
	v_pk_mul_f32 v[44:45], v[66:67], v[44:45] op_sel_hi:[0,1]
	v_pk_mul_f32 v[42:43], v[66:67], v[42:43] op_sel_hi:[0,1]
	v_pk_mul_f32 v[40:41], v[66:67], v[40:41] op_sel_hi:[0,1]
	v_pk_mul_f32 v[38:39], v[66:67], v[38:39] op_sel_hi:[0,1]
	v_pk_mul_f32 v[36:37], v[66:67], v[36:37] op_sel_hi:[0,1]
	v_pk_mul_f32 v[34:35], v[66:67], v[34:35] op_sel_hi:[0,1]
	v_pk_mul_f32 v[32:33], v[66:67], v[32:33] op_sel_hi:[0,1]
	v_pk_mul_f32 v[30:31], v[66:67], v[30:31] op_sel_hi:[0,1]
	v_pk_mul_f32 v[28:29], v[66:67], v[28:29] op_sel_hi:[0,1]
	v_pk_mul_f32 v[26:27], v[66:67], v[26:27] op_sel_hi:[0,1]
	v_pk_mul_f32 v[24:25], v[66:67], v[24:25] op_sel_hi:[0,1]
	v_pk_mul_f32 v[22:23], v[66:67], v[22:23] op_sel_hi:[0,1]
	v_pk_mul_f32 v[20:21], v[66:67], v[20:21] op_sel_hi:[0,1]
	v_pk_mul_f32 v[18:19], v[66:67], v[18:19] op_sel_hi:[0,1]
	v_pk_mul_f32 v[16:17], v[66:67], v[16:17] op_sel_hi:[0,1]
	v_pk_mul_f32 v[14:15], v[66:67], v[14:15] op_sel_hi:[0,1]
	v_pk_mul_f32 v[12:13], v[66:67], v[12:13] op_sel_hi:[0,1]
	v_pk_mul_f32 v[10:11], v[66:67], v[10:11] op_sel_hi:[0,1]
	v_pk_mul_f32 v[8:9], v[66:67], v[8:9] op_sel_hi:[0,1]
	v_pk_mul_f32 v[6:7], v[66:67], v[6:7] op_sel_hi:[0,1]
	v_pk_mul_f32 v[4:5], v[66:67], v[4:5] op_sel_hi:[0,1]
	v_pk_mul_f32 v[2:3], v[66:67], v[2:3] op_sel_hi:[0,1]
	v_mul_f32_e32 v0, v0, v66
	s_branch .LBB0_291
